# attention window mask: v_bitop3 + v_and_or per element replaced by one v_bfi_b32 (same select), MFMA distances re-padded
# speedup vs baseline: 1.0068x; 1.0028x over previous
.LBB0_302:
	v_sub_f32_e32 v39, v39, v170
	v_sub_f32_e32 v38, v38, v170
	v_sub_f32_e32 v37, v37, v170
	v_sub_f32_e32 v35, v35, v170
	v_exp_f32_e32 v39, v39
	v_exp_f32_e32 v38, v38
	v_exp_f32_e32 v37, v37
	v_exp_f32_e32 v35, v35
	v_sub_f32_e32 v210, v210, v170
	v_sub_f32_e32 v209, v209, v170
	v_sub_f32_e32 v34, v34, v170
	v_sub_f32_e32 v32, v32, v170
	v_exp_f32_e32 v210, v210
	v_exp_f32_e32 v209, v209
	v_exp_f32_e32 v34, v34
	v_exp_f32_e32 v32, v32
	v_cvt_pk_bf16_f32 v211, v39, v38
	v_cvt_pk_bf16_f32 v212, v37, v35
	v_mov_b32_e32 v37, v36
	v_mov_b32_e32 v38, v36
	v_mov_b32_e32 v39, v36
	v_cvt_pk_bf16_f32 v210, v210, v209
	v_cvt_pk_bf16_f32 v213, v34, v32
	s_waitcnt vmcnt(11)
	s_nop 0
	v_mfma_f32_16x16x32_bf16 v[72:75], v[0:3], v[210:213], v[72:75]
	s_waitcnt vmcnt(10)
	v_mfma_f32_16x16x32_bf16 v[68:71], v[4:7], v[210:213], v[68:71]
	s_waitcnt vmcnt(9)
	v_mfma_f32_16x16x32_bf16 v[64:67], v[8:11], v[210:213], v[64:67]
	s_waitcnt vmcnt(8)
	v_mfma_f32_16x16x32_bf16 v[60:63], v[12:15], v[210:213], v[60:63]
	v_mfma_f32_16x16x32_bf16 v[76:79], v[36:39], v[210:213], v[76:79]
	ds_read_b128 v[210:213], v161 offset:22528
	ds_read_b128 v[214:217], v161 offset:23552
	ds_read_b32 v218, v208 offset:64
	ds_read_b32 v222, v208 offset:128
	ds_read_b32 v219, v208 offset:68
	ds_read_b32 v223, v208 offset:132
	ds_read_b32 v220, v208 offset:72
	ds_read_b32 v224, v208 offset:136
	ds_read_b32 v221, v208 offset:76
	ds_read_b32 v225, v208 offset:140
	s_waitcnt lgkmcnt(1)
	v_mfma_f32_16x16x32_bf16 v[218:221], v[20:23], v[210:213], v[218:221]
	s_waitcnt lgkmcnt(0)
	v_mfma_f32_16x16x32_bf16 v[210:213], v[28:31], v[210:213], v[222:225]
	v_mfma_f32_16x16x32_bf16 v[210:213], v[24:27], v[214:217], v[210:213]
	v_mfma_f32_16x16x32_bf16 v[218:221], v[16:19], v[214:217], v[218:221]
	s_nop 5
	s_nop 0
	v_bfi_b32 v210, v156, v210, s29
	v_bfi_b32 v211, v157, v211, s29
	v_bfi_b32 v32, v152, v218, s29
	v_bfi_b32 v34, v153, v219, s29
	v_bfi_b32 v212, v158, v212, s29
	v_bfi_b32 v35, v154, v220, s29
	v_bfi_b32 v209, v155, v221, s29
	v_bfi_b32 v213, v159, v213, s29
	v_max3_f32 v214, v210, v211, v32
	v_max3_f32 v216, v34, v212, v35
	v_max3_f32 v214, v214, v209, v213
	v_max_f32_e32 v214, v214, v216
	v_add_f32_e32 v215, 0x41000000, v172
	v_cmp_gt_f32_e32 vcc, v214, v215
	s_cbranch_vccz .LBB0_304
	v_mov_b32_e32 v215, v214
	s_nop 1
	v_permlane16_swap_b32 v214, v215
	s_nop 0
	v_max_f32_e32 v215, v215, v215
	v_max_f32_e32 v214, v214, v214
	v_max_f32_e32 v214, v214, v215
	v_mov_b32_e32 v215, v214
	s_nop 1
	v_permlane32_swap_b32 v214, v215
	s_nop 0
	v_max3_f32 v214, v172, v214, v215
	v_sub_f32_e32 v172, v172, v214
	v_exp_f32_e32 v172, v172
	s_nop 0
	v_pk_mul_f32 v[114:115], v[114:115], v[172:173] op_sel_hi:[1,0]
	v_pk_mul_f32 v[112:113], v[112:113], v[172:173] op_sel_hi:[1,0]
	v_pk_mul_f32 v[110:111], v[110:111], v[172:173] op_sel_hi:[1,0]
	v_pk_mul_f32 v[108:109], v[108:109], v[172:173] op_sel_hi:[1,0]
	v_pk_mul_f32 v[106:107], v[106:107], v[172:173] op_sel_hi:[1,0]
	v_pk_mul_f32 v[104:105], v[104:105], v[172:173] op_sel_hi:[1,0]
	v_pk_mul_f32 v[102:103], v[102:103], v[172:173] op_sel_hi:[1,0]
	v_pk_mul_f32 v[100:101], v[100:101], v[172:173] op_sel_hi:[1,0]
	v_pk_mul_f32 v[118:119], v[118:119], v[172:173] op_sel_hi:[1,0]
	v_pk_mul_f32 v[116:117], v[116:117], v[172:173] op_sel_hi:[1,0]
	v_mov_b32_e32 v172, v214
.LBB0_304:
	v_sub_f32_e32 v210, v210, v172
	v_exp_f32_e32 v214, v210
	v_sub_f32_e32 v210, v211, v172
	v_exp_f32_e32 v215, v210
	v_sub_f32_e32 v210, v212, v172
	v_sub_f32_e32 v32, v32, v172
	v_sub_f32_e32 v34, v34, v172
	v_sub_f32_e32 v35, v35, v172
	v_sub_f32_e32 v209, v209, v172
	v_exp_f32_e32 v216, v210
	v_sub_f32_e32 v210, v213, v172
	v_exp_f32_e32 v32, v32
	v_exp_f32_e32 v34, v34
	v_exp_f32_e32 v35, v35
	v_exp_f32_e32 v209, v209
	v_exp_f32_e32 v213, v210
	v_cvt_pk_bf16_f32 v210, v32, v34
	v_cvt_pk_bf16_f32 v212, v214, v215
	v_cvt_pk_bf16_f32 v211, v35, v209
	v_cvt_pk_bf16_f32 v213, v216, v213
	s_nop 1
	v_mfma_f32_16x16x32_bf16 v[112:115], v[0:3], v[210:213], v[112:115]
	v_mfma_f32_16x16x32_bf16 v[108:111], v[4:7], v[210:213], v[108:111]
	v_mfma_f32_16x16x32_bf16 v[104:107], v[8:11], v[210:213], v[104:107]
	v_mfma_f32_16x16x32_bf16 v[100:103], v[12:15], v[210:213], v[100:103]
	v_mfma_f32_16x16x32_bf16 v[116:119], v[36:39], v[210:213], v[116:119]
	ds_read_b128 v[210:213], v161 offset:24576
	ds_read_b128 v[214:217], v161 offset:25600
	ds_read_b32 v218, v208
	ds_read_b32 v222, v208 offset:64
	ds_read_b32 v219, v208 offset:4
	ds_read_b32 v223, v208 offset:68
	ds_read_b32 v220, v208 offset:8
	ds_read_b32 v224, v208 offset:72
	ds_read_b32 v221, v208 offset:12
	ds_read_b32 v225, v208 offset:76
	s_waitcnt lgkmcnt(1)
	v_mfma_f32_16x16x32_bf16 v[20:23], v[20:23], v[210:213], v[218:221]
	v_mfma_f32_16x16x32_bf16 v[16:19], v[16:19], v[214:217], v[20:23]
	s_waitcnt lgkmcnt(0)
	s_nop 5
	v_mfma_f32_16x16x32_bf16 v[20:23], v[28:31], v[210:213], v[222:225]
	v_mfma_f32_16x16x32_bf16 v[20:23], v[24:27], v[214:217], v[20:23]
	s_nop 3
	v_bfi_b32 v17, v173, v17, s29
	v_bfi_b32 v18, v174, v18, s29
	v_bfi_b32 v19, v175, v19, s29
	s_nop 0
	v_bfi_b32 v20, v176, v20, s29
	v_bfi_b32 v21, v177, v21, s29
	v_cndmask_b32_e64 v16, v242, v16, s[58:59]
	v_bfi_b32 v22, v178, v22, s29
	v_bfi_b32 v23, v183, v23, s29
	v_max3_f32 v24, v17, v18, v19
	v_max3_f32 v26, v20, v21, v16
	v_max3_f32 v24, v24, v22, v23
	v_max_f32_e32 v24, v24, v26
	v_add_f32_e32 v25, 0x41000000, v171
	v_cmp_gt_f32_e32 vcc, v24, v25
	s_cbranch_vccz .LBB0_306
	v_mov_b32_e32 v25, v24
	s_nop 1
	v_permlane16_swap_b32 v24, v25
	s_nop 0
	v_max_f32_e32 v25, v25, v25
	v_max_f32_e32 v24, v24, v24
	v_max_f32_e32 v24, v24, v25
	v_mov_b32_e32 v25, v24
	s_nop 1
	v_permlane32_swap_b32 v25, v24
	s_nop 0
	v_max3_f32 v25, v171, v25, v24
	v_sub_f32_e32 v24, v171, v25
	v_exp_f32_e32 v24, v24
	v_mov_b32_e32 v171, v25
	v_pk_mul_f32 v[94:95], v[94:95], v[24:25] op_sel_hi:[1,0]
	v_pk_mul_f32 v[92:93], v[92:93], v[24:25] op_sel_hi:[1,0]
	v_pk_mul_f32 v[90:91], v[90:91], v[24:25] op_sel_hi:[1,0]
	v_pk_mul_f32 v[88:89], v[88:89], v[24:25] op_sel_hi:[1,0]
	v_pk_mul_f32 v[86:87], v[86:87], v[24:25] op_sel_hi:[1,0]
	v_pk_mul_f32 v[84:85], v[84:85], v[24:25] op_sel_hi:[1,0]
	v_pk_mul_f32 v[82:83], v[82:83], v[24:25] op_sel_hi:[1,0]
	v_pk_mul_f32 v[80:81], v[80:81], v[24:25] op_sel_hi:[1,0]
	v_pk_mul_f32 v[98:99], v[98:99], v[24:25] op_sel_hi:[1,0]
	v_pk_mul_f32 v[96:97], v[96:97], v[24:25] op_sel_hi:[1,0]
.LBB0_306:
	v_sub_f32_e32 v16, v16, v171
	v_sub_f32_e32 v17, v17, v171
	v_sub_f32_e32 v18, v18, v171
	v_sub_f32_e32 v19, v19, v171
	v_sub_f32_e32 v20, v20, v171
	v_sub_f32_e32 v21, v21, v171
	v_sub_f32_e32 v22, v22, v171
	v_sub_f32_e32 v23, v23, v171
	v_exp_f32_e32 v16, v16
	v_exp_f32_e32 v17, v17
	v_exp_f32_e32 v18, v18
	v_exp_f32_e32 v19, v19
	v_exp_f32_e32 v20, v20
	v_exp_f32_e32 v21, v21
	v_exp_f32_e32 v22, v22
	v_exp_f32_e32 v23, v23
	v_mov_b32_e32 v37, v36
	v_mov_b32_e32 v38, v36
	v_mov_b32_e32 v39, v36
	v_cvt_pk_bf16_f32 v16, v16, v17
	v_cvt_pk_bf16_f32 v17, v18, v19
	v_cvt_pk_bf16_f32 v18, v20, v21
	v_cvt_pk_bf16_f32 v19, v22, v23
	s_nop 1
	v_mfma_f32_16x16x32_bf16 v[92:95], v[0:3], v[16:19], v[92:95]
	v_mfma_f32_16x16x32_bf16 v[88:91], v[4:7], v[16:19], v[88:91]
	v_mfma_f32_16x16x32_bf16 v[84:87], v[8:11], v[16:19], v[84:87]
	v_mfma_f32_16x16x32_bf16 v[80:83], v[12:15], v[16:19], v[80:83]
	v_mfma_f32_16x16x32_bf16 v[96:99], v[36:39], v[16:19], v[96:99]
	s_add_i32 s27, s27, 2
	s_cmp_eq_u32 s25, 14
	s_cselect_b32 s30, s24, s27
	s_lshl_b32 s62, s30, 1
	s_mov_b32 s63, s1
	s_lshl_b64 s[62:63], s[62:63], 14
	v_lshl_add_u64 v[0:1], v[164:165], 0, s[62:63]
	s_mov_b32 s31, s1
	s_lshl_b64 s[30:31], s[30:31], 15
	global_load_dwordx4 v[20:23], v[0:1], off
	global_load_dwordx4 v[16:19], v[0:1], off offset:1024
	v_add_co_u32_e32 v0, vcc, s72, v0
	v_lshl_add_u64 v[12:13], v[166:167], 0, s[30:31]
	s_nop 0
	v_addc_co_u32_e32 v1, vcc, 0, v1, vcc
	global_load_dwordx4 v[28:31], v[0:1], off
	global_load_dwordx4 v[24:27], v[0:1], off offset:1024
	s_nop 0
	global_load_dwordx4 v[0:3], v[12:13], off
	global_load_dwordx4 v[4:7], v[12:13], off offset:1024
	global_load_dwordx4 v[8:11], v[12:13], off offset:2048
	s_nop 0
	global_load_dwordx4 v[12:15], v[12:13], off offset:3072
	ds_read_b128 v[210:213], v161 offset:22528
	ds_read_b128 v[214:217], v161 offset:23552
	ds_read_b32 v218, v208 offset:192
	ds_read_b32 v222, v208 offset:256
	ds_read_b32 v219, v208 offset:196
	ds_read_b32 v223, v208 offset:260
	ds_read_b32 v220, v208 offset:200
	ds_read_b32 v224, v208 offset:264
	ds_read_b32 v221, v208 offset:204
	ds_read_b32 v225, v208 offset:268
	s_waitcnt vmcnt(15) lgkmcnt(1)
	v_mfma_f32_16x16x32_bf16 v[218:221], v[136:139], v[210:213], v[218:221]
	s_waitcnt vmcnt(13) lgkmcnt(0)
	v_mfma_f32_16x16x32_bf16 v[210:213], v[148:151], v[210:213], v[222:225]
	s_waitcnt vmcnt(12)
	v_mfma_f32_16x16x32_bf16 v[210:213], v[144:147], v[214:217], v[210:213]
	v_mfma_f32_16x16x32_bf16 v[218:221], v[140:143], v[214:217], v[218:221]
	s_nop 5
	s_nop 0
	v_bfi_b32 v210, v188, v210, s29
	v_bfi_b32 v211, v189, v211, s29
	v_bfi_b32 v32, v184, v218, s29
	v_bfi_b32 v34, v185, v219, s29
	v_bfi_b32 v212, v190, v212, s29
	v_bfi_b32 v35, v186, v220, s29
	v_bfi_b32 v209, v187, v221, s29
	v_bfi_b32 v213, v191, v213, s29
	v_max3_f32 v214, v210, v211, v32
	v_max3_f32 v216, v34, v212, v35
	v_max3_f32 v214, v214, v209, v213
	v_max_f32_e32 v214, v214, v216
	v_add_f32_e32 v215, 0x41000000, v172
	v_cmp_gt_f32_e32 vcc, v214, v215
	s_cbranch_vccz .LBB0_308
	v_mov_b32_e32 v215, v214
	s_nop 1
	v_permlane16_swap_b32 v214, v215
	s_nop 0
	v_max_f32_e32 v215, v215, v215
	v_max_f32_e32 v214, v214, v214
	v_max_f32_e32 v214, v214, v215
	v_mov_b32_e32 v215, v214
	s_nop 1
	v_permlane32_swap_b32 v214, v215
	s_nop 0
	v_max3_f32 v214, v172, v214, v215
	v_sub_f32_e32 v172, v172, v214
	v_exp_f32_e32 v172, v172
	s_nop 0
	v_pk_mul_f32 v[114:115], v[114:115], v[172:173] op_sel_hi:[1,0]
	v_pk_mul_f32 v[112:113], v[112:113], v[172:173] op_sel_hi:[1,0]
	v_pk_mul_f32 v[110:111], v[110:111], v[172:173] op_sel_hi:[1,0]
	v_pk_mul_f32 v[108:109], v[108:109], v[172:173] op_sel_hi:[1,0]
	v_pk_mul_f32 v[106:107], v[106:107], v[172:173] op_sel_hi:[1,0]
	v_pk_mul_f32 v[104:105], v[104:105], v[172:173] op_sel_hi:[1,0]
	v_pk_mul_f32 v[102:103], v[102:103], v[172:173] op_sel_hi:[1,0]
	v_pk_mul_f32 v[100:101], v[100:101], v[172:173] op_sel_hi:[1,0]
	v_pk_mul_f32 v[118:119], v[118:119], v[172:173] op_sel_hi:[1,0]
	v_pk_mul_f32 v[116:117], v[116:117], v[172:173] op_sel_hi:[1,0]
	v_mov_b32_e32 v172, v214
.LBB0_308:
	v_sub_f32_e32 v210, v210, v172
	v_exp_f32_e32 v214, v210
	v_sub_f32_e32 v210, v211, v172
	v_exp_f32_e32 v215, v210
	v_sub_f32_e32 v210, v212, v172
	v_sub_f32_e32 v32, v32, v172
	v_sub_f32_e32 v34, v34, v172
	v_sub_f32_e32 v35, v35, v172
	v_sub_f32_e32 v209, v209, v172
	v_exp_f32_e32 v216, v210
	v_sub_f32_e32 v210, v213, v172
	v_exp_f32_e32 v32, v32
	v_exp_f32_e32 v34, v34
	v_exp_f32_e32 v35, v35
	v_exp_f32_e32 v209, v209
	v_exp_f32_e32 v213, v210
	v_cvt_pk_bf16_f32 v210, v32, v34
	v_cvt_pk_bf16_f32 v212, v214, v215
	v_cvt_pk_bf16_f32 v211, v35, v209
	v_cvt_pk_bf16_f32 v213, v216, v213
	s_waitcnt vmcnt(11)
	s_nop 0
	v_mfma_f32_16x16x32_bf16 v[112:115], v[120:123], v[210:213], v[112:115]
	s_waitcnt vmcnt(10)
	v_mfma_f32_16x16x32_bf16 v[108:111], v[124:127], v[210:213], v[108:111]
	s_waitcnt vmcnt(9)
	v_mfma_f32_16x16x32_bf16 v[104:107], v[128:131], v[210:213], v[104:107]
	s_waitcnt vmcnt(8)
	v_mfma_f32_16x16x32_bf16 v[100:103], v[132:135], v[210:213], v[100:103]
	v_mfma_f32_16x16x32_bf16 v[116:119], v[36:39], v[210:213], v[116:119]
	ds_read_b128 v[210:213], v161 offset:24576
	ds_read_b128 v[214:217], v161 offset:25600
	ds_read_b32 v218, v208 offset:128
	ds_read_b32 v222, v208 offset:192
	ds_read_b32 v219, v208 offset:132
	ds_read_b32 v223, v208 offset:196
	ds_read_b32 v220, v208 offset:136
	ds_read_b32 v224, v208 offset:200
	ds_read_b32 v221, v208 offset:140
	ds_read_b32 v225, v208 offset:204
	s_waitcnt lgkmcnt(1)
	v_mfma_f32_16x16x32_bf16 v[218:221], v[136:139], v[210:213], v[218:221]
	s_waitcnt lgkmcnt(0)
	v_mfma_f32_16x16x32_bf16 v[210:213], v[148:151], v[210:213], v[222:225]
	v_mfma_f32_16x16x32_bf16 v[218:221], v[140:143], v[214:217], v[218:221]
	v_mfma_f32_16x16x32_bf16 v[210:213], v[144:147], v[214:217], v[210:213]
	s_nop 6
	v_bfi_b32 v32, v192, v218, s29
	v_bfi_b32 v34, v193, v219, s29
	v_bfi_b32 v35, v194, v220, s29
	v_bfi_b32 v37, v195, v221, s29
	v_bfi_b32 v38, v196, v210, s29
	v_bfi_b32 v39, v197, v211, s29
	v_bfi_b32 v209, v198, v212, s29
	v_bfi_b32 v210, v199, v213, s29
	v_max3_f32 v211, v32, v34, v35
	v_max3_f32 v213, v37, v38, v39
	v_max3_f32 v211, v211, v209, v210
	v_max_f32_e32 v211, v211, v213
	v_add_f32_e32 v212, 0x41000000, v171
	v_cmp_gt_f32_e32 vcc, v211, v212
	s_cbranch_vccz .LBB0_310
	v_mov_b32_e32 v212, v211
	s_nop 1
	v_permlane16_swap_b32 v211, v212
	s_nop 0
	v_max_f32_e32 v212, v212, v212
	v_max_f32_e32 v211, v211, v211
	v_max_f32_e32 v211, v211, v212
	v_mov_b32_e32 v212, v211
	s_nop 1
	v_permlane32_swap_b32 v211, v212
	s_nop 0
	v_max3_f32 v211, v171, v211, v212
	v_sub_f32_e32 v171, v171, v211
	v_exp_f32_e32 v212, v171
	v_mov_b32_e32 v171, v211
	v_pk_mul_f32 v[94:95], v[94:95], v[212:213] op_sel_hi:[1,0]
	v_pk_mul_f32 v[92:93], v[92:93], v[212:213] op_sel_hi:[1,0]
	v_pk_mul_f32 v[90:91], v[90:91], v[212:213] op_sel_hi:[1,0]
	v_pk_mul_f32 v[88:89], v[88:89], v[212:213] op_sel_hi:[1,0]
	v_pk_mul_f32 v[86:87], v[86:87], v[212:213] op_sel_hi:[1,0]
	v_pk_mul_f32 v[84:85], v[84:85], v[212:213] op_sel_hi:[1,0]
	v_pk_mul_f32 v[82:83], v[82:83], v[212:213] op_sel_hi:[1,0]
	v_pk_mul_f32 v[80:81], v[80:81], v[212:213] op_sel_hi:[1,0]
	v_pk_mul_f32 v[98:99], v[98:99], v[212:213] op_sel_hi:[1,0]
	v_pk_mul_f32 v[96:97], v[96:97], v[212:213] op_sel_hi:[1,0]
.LBB0_310:
	v_sub_f32_e32 v35, v35, v171
	v_sub_f32_e32 v37, v37, v171
	v_sub_f32_e32 v38, v38, v171
	v_sub_f32_e32 v39, v39, v171
	v_exp_f32_e32 v35, v35
	v_exp_f32_e32 v37, v37
	v_exp_f32_e32 v38, v38
	v_exp_f32_e32 v39, v39
	v_sub_f32_e32 v32, v32, v171
	v_sub_f32_e32 v34, v34, v171
	v_sub_f32_e32 v209, v209, v171
	v_sub_f32_e32 v210, v210, v171
	v_exp_f32_e32 v32, v32
	v_exp_f32_e32 v34, v34
	v_exp_f32_e32 v209, v209
	v_exp_f32_e32 v213, v210
	v_cvt_pk_bf16_f32 v211, v35, v37
	v_cvt_pk_bf16_f32 v212, v38, v39
	v_mov_b32_e32 v37, v36
	v_mov_b32_e32 v38, v36
	v_mov_b32_e32 v39, v36
	v_cvt_pk_bf16_f32 v210, v32, v34
	v_cvt_pk_bf16_f32 v213, v209, v213
	s_nop 1
	v_mfma_f32_16x16x32_bf16 v[92:95], v[120:123], v[210:213], v[92:95]
	v_mfma_f32_16x16x32_bf16 v[88:91], v[124:127], v[210:213], v[88:91]
	v_mfma_f32_16x16x32_bf16 v[84:87], v[128:131], v[210:213], v[84:87]
	v_mfma_f32_16x16x32_bf16 v[80:83], v[132:135], v[210:213], v[80:83]
	v_mfma_f32_16x16x32_bf16 v[96:99], v[36:39], v[210:213], v[96:99]
	ds_read_b128 v[210:213], v161 offset:26624
	ds_read_b128 v[214:217], v161 offset:27648
	ds_read_b32 v218, v208 offset:64
	ds_read_b32 v222, v208 offset:128
	ds_read_b32 v219, v208 offset:68
	ds_read_b32 v223, v208 offset:132
	ds_read_b32 v220, v208 offset:72
	ds_read_b32 v224, v208 offset:136
	ds_read_b32 v221, v208 offset:76
	ds_read_b32 v225, v208 offset:140
	s_waitcnt lgkmcnt(1)
	v_mfma_f32_16x16x32_bf16 v[136:139], v[136:139], v[210:213], v[218:221]
	v_mfma_f32_16x16x32_bf16 v[136:139], v[140:143], v[214:217], v[136:139]
	s_waitcnt lgkmcnt(0)
	v_mfma_f32_16x16x32_bf16 v[140:143], v[148:151], v[210:213], v[222:225]
	v_mfma_f32_16x16x32_bf16 v[140:143], v[144:147], v[214:217], v[140:143]
	s_nop 4
	v_bfi_b32 v32, v200, v136, s29
	v_bfi_b32 v34, v201, v137, s29
	v_bfi_b32 v35, v202, v138, s29
	v_bfi_b32 v136, v203, v139, s29
	v_bfi_b32 v137, v204, v140, s29
	v_bfi_b32 v138, v205, v141, s29
	v_bfi_b32 v139, v206, v142, s29
	v_bfi_b32 v140, v207, v143, s29
	v_max3_f32 v141, v32, v34, v35
	v_max3_f32 v143, v136, v137, v138
	v_max3_f32 v141, v141, v139, v140
	v_max_f32_e32 v141, v141, v143
	v_add_f32_e32 v142, 0x41000000, v169
	v_cmp_gt_f32_e32 vcc, v141, v142
	s_cbranch_vccz .LBB0_299
	v_mov_b32_e32 v142, v141
	s_nop 1
	v_permlane16_swap_b32 v141, v142
	s_nop 0
	v_max_f32_e32 v142, v142, v142
	v_max_f32_e32 v141, v141, v141
	v_max_f32_e32 v141, v141, v142
	v_mov_b32_e32 v142, v141
	s_nop 1
	v_permlane32_swap_b32 v141, v142
	s_nop 0
	v_max3_f32 v141, v169, v141, v142
	v_sub_f32_e32 v142, v169, v141
	v_exp_f32_e32 v142, v142
	v_mov_b32_e32 v169, v141
	v_pk_mul_f32 v[54:55], v[54:55], v[142:143] op_sel_hi:[1,0]
	v_pk_mul_f32 v[52:53], v[52:53], v[142:143] op_sel_hi:[1,0]
	v_pk_mul_f32 v[50:51], v[50:51], v[142:143] op_sel_hi:[1,0]
	v_pk_mul_f32 v[48:49], v[48:49], v[142:143] op_sel_hi:[1,0]
	v_pk_mul_f32 v[46:47], v[46:47], v[142:143] op_sel_hi:[1,0]
	v_pk_mul_f32 v[44:45], v[44:45], v[142:143] op_sel_hi:[1,0]
	v_pk_mul_f32 v[42:43], v[42:43], v[142:143] op_sel_hi:[1,0]
	v_pk_mul_f32 v[40:41], v[40:41], v[142:143] op_sel_hi:[1,0]
	v_pk_mul_f32 v[58:59], v[58:59], v[142:143] op_sel_hi:[1,0]
	v_pk_mul_f32 v[56:57], v[56:57], v[142:143] op_sel_hi:[1,0]
	s_branch .LBB0_299

.LBB0_351:
	v_sub_f32_e32 v39, v39, v170
	v_sub_f32_e32 v38, v38, v170
	v_sub_f32_e32 v37, v37, v170
	v_sub_f32_e32 v35, v35, v170
	v_exp_f32_e32 v39, v39
	v_exp_f32_e32 v38, v38
	v_exp_f32_e32 v37, v37
	v_exp_f32_e32 v35, v35
	v_sub_f32_e32 v214, v214, v170
	v_sub_f32_e32 v213, v213, v170
	v_sub_f32_e32 v34, v34, v170
	v_sub_f32_e32 v32, v32, v170
	v_exp_f32_e32 v214, v214
	v_exp_f32_e32 v213, v213
	v_exp_f32_e32 v34, v34
	v_exp_f32_e32 v32, v32
	v_cvt_pk_bf16_f32 v215, v39, v38
	v_cvt_pk_bf16_f32 v216, v37, v35
	v_mov_b32_e32 v37, v36
	v_mov_b32_e32 v38, v36
	v_mov_b32_e32 v39, v36
	v_cvt_pk_bf16_f32 v214, v214, v213
	v_cvt_pk_bf16_f32 v217, v34, v32
	s_waitcnt vmcnt(11)
	s_nop 0
	v_mfma_f32_16x16x32_bf16 v[72:75], v[0:3], v[214:217], v[72:75]
	s_waitcnt vmcnt(10)
	v_mfma_f32_16x16x32_bf16 v[68:71], v[4:7], v[214:217], v[68:71]
	s_waitcnt vmcnt(9)
	v_mfma_f32_16x16x32_bf16 v[64:67], v[8:11], v[214:217], v[64:67]
	s_waitcnt vmcnt(8)
	v_mfma_f32_16x16x32_bf16 v[60:63], v[12:15], v[214:217], v[60:63]
	v_mfma_f32_16x16x32_bf16 v[76:79], v[36:39], v[214:217], v[76:79]
	ds_read_b128 v[214:217], v168 offset:22528
	ds_read_b128 v[218:221], v168 offset:23552
	ds_read_b32 v222, v212 offset:64
	ds_read_b32 v246, v212 offset:128
	ds_read_b32 v223, v212 offset:68
	ds_read_b32 v247, v212 offset:132
	ds_read_b32 v224, v212 offset:72
	ds_read_b32 v248, v212 offset:136
	ds_read_b32 v225, v212 offset:76
	ds_read_b32 v249, v212 offset:140
	s_waitcnt lgkmcnt(1)
	v_mfma_f32_16x16x32_bf16 v[222:225], v[24:27], v[214:217], v[222:225]
	s_waitcnt lgkmcnt(0)
	v_mfma_f32_16x16x32_bf16 v[214:217], v[28:31], v[214:217], v[246:249]
	v_mfma_f32_16x16x32_bf16 v[214:217], v[20:23], v[218:221], v[214:217]
	v_mfma_f32_16x16x32_bf16 v[222:225], v[16:19], v[218:221], v[222:225]
	s_nop 5
	s_nop 0
	v_bfi_b32 v214, v173, v214, s29
	v_bfi_b32 v215, v174, v215, s29
	v_bfi_b32 v32, v156, v222, s29
	v_bfi_b32 v34, v157, v223, s29
	v_bfi_b32 v216, v175, v216, s29
	v_bfi_b32 v35, v158, v224, s29
	v_bfi_b32 v213, v159, v225, s29
	v_bfi_b32 v217, v176, v217, s29
	v_max3_f32 v218, v214, v215, v32
	v_max3_f32 v220, v34, v216, v35
	v_max3_f32 v218, v218, v213, v217
	v_max_f32_e32 v218, v218, v220
	v_add_f32_e32 v219, 0x41000000, v172
	v_cmp_gt_f32_e32 vcc, v218, v219
	s_cbranch_vccz .LBB0_353
	v_mov_b32_e32 v219, v218
	s_nop 1
	v_permlane16_swap_b32 v218, v219
	s_nop 0
	v_max_f32_e32 v219, v219, v219
	v_max_f32_e32 v218, v218, v218
	v_max_f32_e32 v218, v218, v219
	v_mov_b32_e32 v219, v218
	s_nop 1
	v_permlane32_swap_b32 v218, v219
	s_nop 0
	v_max3_f32 v218, v172, v218, v219
	v_sub_f32_e32 v172, v172, v218
	v_exp_f32_e32 v172, v172
	s_nop 0
	v_pk_mul_f32 v[114:115], v[114:115], v[172:173] op_sel_hi:[1,0]
	v_pk_mul_f32 v[112:113], v[112:113], v[172:173] op_sel_hi:[1,0]
	v_pk_mul_f32 v[110:111], v[110:111], v[172:173] op_sel_hi:[1,0]
	v_pk_mul_f32 v[108:109], v[108:109], v[172:173] op_sel_hi:[1,0]
	v_pk_mul_f32 v[106:107], v[106:107], v[172:173] op_sel_hi:[1,0]
	v_pk_mul_f32 v[104:105], v[104:105], v[172:173] op_sel_hi:[1,0]
	v_pk_mul_f32 v[102:103], v[102:103], v[172:173] op_sel_hi:[1,0]
	v_pk_mul_f32 v[100:101], v[100:101], v[172:173] op_sel_hi:[1,0]
	v_pk_mul_f32 v[118:119], v[118:119], v[172:173] op_sel_hi:[1,0]
	v_pk_mul_f32 v[116:117], v[116:117], v[172:173] op_sel_hi:[1,0]
	v_mov_b32_e32 v172, v218
.LBB0_353:
	v_sub_f32_e32 v214, v214, v172
	v_exp_f32_e32 v218, v214
	v_sub_f32_e32 v214, v215, v172
	v_exp_f32_e32 v219, v214
	v_sub_f32_e32 v214, v216, v172
	v_sub_f32_e32 v32, v32, v172
	v_sub_f32_e32 v34, v34, v172
	v_sub_f32_e32 v35, v35, v172
	v_sub_f32_e32 v213, v213, v172
	v_exp_f32_e32 v220, v214
	v_sub_f32_e32 v214, v217, v172
	v_exp_f32_e32 v32, v32
	v_exp_f32_e32 v34, v34
	v_exp_f32_e32 v35, v35
	v_exp_f32_e32 v213, v213
	v_exp_f32_e32 v217, v214
	v_cvt_pk_bf16_f32 v214, v32, v34
	v_cvt_pk_bf16_f32 v216, v218, v219
	v_cvt_pk_bf16_f32 v215, v35, v213
	v_cvt_pk_bf16_f32 v217, v220, v217
	s_nop 1
	v_mfma_f32_16x16x32_bf16 v[112:115], v[0:3], v[214:217], v[112:115]
	v_mfma_f32_16x16x32_bf16 v[108:111], v[4:7], v[214:217], v[108:111]
	v_mfma_f32_16x16x32_bf16 v[104:107], v[8:11], v[214:217], v[104:107]
	v_mfma_f32_16x16x32_bf16 v[100:103], v[12:15], v[214:217], v[100:103]
	v_mfma_f32_16x16x32_bf16 v[116:119], v[36:39], v[214:217], v[116:119]
	ds_read_b128 v[214:217], v168 offset:24576
	ds_read_b128 v[218:221], v168 offset:25600
	ds_read_b32 v222, v212
	ds_read_b32 v246, v212 offset:64
	ds_read_b32 v223, v212 offset:4
	ds_read_b32 v247, v212 offset:68
	ds_read_b32 v224, v212 offset:8
	ds_read_b32 v248, v212 offset:72
	ds_read_b32 v225, v212 offset:12
	ds_read_b32 v249, v212 offset:76
	s_waitcnt lgkmcnt(1)
	v_mfma_f32_16x16x32_bf16 v[24:27], v[24:27], v[214:217], v[222:225]
	v_mfma_f32_16x16x32_bf16 v[16:19], v[16:19], v[218:221], v[24:27]
	s_waitcnt lgkmcnt(0)
	s_nop 5
	v_mfma_f32_16x16x32_bf16 v[24:27], v[28:31], v[214:217], v[246:249]
	v_mfma_f32_16x16x32_bf16 v[20:23], v[20:23], v[218:221], v[24:27]
	s_nop 4
	v_cndmask_b32_e64 v16, v242, v16, s[58:59]
	s_nop 0
	v_bfi_b32 v17, v177, v17, s29
	v_bfi_b32 v18, v178, v18, s29
	v_bfi_b32 v19, v183, v19, s29
	v_bfi_b32 v20, v184, v20, s29
	v_bfi_b32 v21, v185, v21, s29
	v_bfi_b32 v22, v186, v22, s29
	v_bfi_b32 v23, v187, v23, s29
	v_max3_f32 v24, v16, v17, v18
	v_max3_f32 v26, v19, v20, v21
	v_max3_f32 v24, v24, v22, v23
	v_max_f32_e32 v24, v24, v26
	v_add_f32_e32 v25, 0x41000000, v171
	v_cmp_gt_f32_e32 vcc, v24, v25
	s_cbranch_vccz .LBB0_355
	v_mov_b32_e32 v25, v24
	s_nop 1
	v_permlane16_swap_b32 v24, v25
	s_nop 0
	v_max_f32_e32 v25, v25, v25
	v_max_f32_e32 v24, v24, v24
	v_max_f32_e32 v24, v24, v25
	v_mov_b32_e32 v25, v24
	s_nop 1
	v_permlane32_swap_b32 v24, v25
	s_nop 0
	v_max3_f32 v25, v171, v24, v25
	v_sub_f32_e32 v24, v171, v25
	v_exp_f32_e32 v24, v24
	v_mov_b32_e32 v171, v25
	v_pk_mul_f32 v[94:95], v[94:95], v[24:25] op_sel_hi:[1,0]
	v_pk_mul_f32 v[92:93], v[92:93], v[24:25] op_sel_hi:[1,0]
	v_pk_mul_f32 v[90:91], v[90:91], v[24:25] op_sel_hi:[1,0]
	v_pk_mul_f32 v[88:89], v[88:89], v[24:25] op_sel_hi:[1,0]
	v_pk_mul_f32 v[86:87], v[86:87], v[24:25] op_sel_hi:[1,0]
	v_pk_mul_f32 v[84:85], v[84:85], v[24:25] op_sel_hi:[1,0]
	v_pk_mul_f32 v[82:83], v[82:83], v[24:25] op_sel_hi:[1,0]
	v_pk_mul_f32 v[80:81], v[80:81], v[24:25] op_sel_hi:[1,0]
	v_pk_mul_f32 v[98:99], v[98:99], v[24:25] op_sel_hi:[1,0]
	v_pk_mul_f32 v[96:97], v[96:97], v[24:25] op_sel_hi:[1,0]
.LBB0_355:
	v_sub_f32_e32 v16, v16, v171
	v_sub_f32_e32 v17, v17, v171
	v_sub_f32_e32 v18, v18, v171
	v_sub_f32_e32 v19, v19, v171
	v_sub_f32_e32 v20, v20, v171
	v_sub_f32_e32 v21, v21, v171
	v_sub_f32_e32 v22, v22, v171
	v_sub_f32_e32 v23, v23, v171
	v_exp_f32_e32 v16, v16
	v_exp_f32_e32 v17, v17
	v_exp_f32_e32 v18, v18
	v_exp_f32_e32 v19, v19
	v_exp_f32_e32 v20, v20
	v_exp_f32_e32 v21, v21
	v_exp_f32_e32 v22, v22
	v_exp_f32_e32 v23, v23
	v_mov_b32_e32 v37, v36
	v_mov_b32_e32 v38, v36
	v_mov_b32_e32 v39, v36
	v_cvt_pk_bf16_f32 v16, v16, v17
	v_cvt_pk_bf16_f32 v17, v18, v19
	v_cvt_pk_bf16_f32 v18, v20, v21
	v_cvt_pk_bf16_f32 v19, v22, v23
	s_nop 1
	v_mfma_f32_16x16x32_bf16 v[92:95], v[0:3], v[16:19], v[92:95]
	v_mfma_f32_16x16x32_bf16 v[88:91], v[4:7], v[16:19], v[88:91]
	v_mfma_f32_16x16x32_bf16 v[84:87], v[8:11], v[16:19], v[84:87]
	v_mfma_f32_16x16x32_bf16 v[80:83], v[12:15], v[16:19], v[80:83]
	v_mfma_f32_16x16x32_bf16 v[96:99], v[36:39], v[16:19], v[96:99]
	s_cmp_eq_u32 s34, 0x70000
	s_cselect_b32 s40, s60, s30
	s_lshl_b32 s0, s40, 1
	s_lshl_b64 s[60:61], s[0:1], 14
	v_lshl_add_u64 v[0:1], v[164:165], 0, s[60:61]
	s_mov_b32 s41, s1
	s_lshl_b64 s[40:41], s[40:41], 15
	global_load_dwordx4 v[24:27], v[0:1], off
	global_load_dwordx4 v[16:19], v[0:1], off offset:1024
	v_add_co_u32_e32 v0, vcc, s72, v0
	v_lshl_add_u64 v[12:13], v[166:167], 0, s[40:41]
	s_nop 0
	v_addc_co_u32_e32 v1, vcc, 0, v1, vcc
	global_load_dwordx4 v[28:31], v[0:1], off
	global_load_dwordx4 v[20:23], v[0:1], off offset:1024
	s_nop 0
	global_load_dwordx4 v[0:3], v[12:13], off
	global_load_dwordx4 v[4:7], v[12:13], off offset:1024
	global_load_dwordx4 v[8:11], v[12:13], off offset:2048
	s_nop 0
	global_load_dwordx4 v[12:15], v[12:13], off offset:3072
	ds_read_b128 v[214:217], v168 offset:22528
	ds_read_b128 v[218:221], v168 offset:23552
	ds_read_b32 v222, v212 offset:192
	ds_read_b32 v246, v212 offset:256
	ds_read_b32 v223, v212 offset:196
	ds_read_b32 v247, v212 offset:260
	ds_read_b32 v224, v212 offset:200
	ds_read_b32 v248, v212 offset:264
	ds_read_b32 v225, v212 offset:204
	ds_read_b32 v249, v212 offset:268
	s_waitcnt vmcnt(15) lgkmcnt(1)
	v_mfma_f32_16x16x32_bf16 v[222:225], v[136:139], v[214:217], v[222:225]
	s_waitcnt vmcnt(13) lgkmcnt(0)
	v_mfma_f32_16x16x32_bf16 v[214:217], v[148:151], v[214:217], v[246:249]
	s_waitcnt vmcnt(12)
	v_mfma_f32_16x16x32_bf16 v[214:217], v[144:147], v[218:221], v[214:217]
	v_mfma_f32_16x16x32_bf16 v[222:225], v[140:143], v[218:221], v[222:225]
	s_nop 5
	s_nop 0
	v_bfi_b32 v214, v192, v214, s29
	v_bfi_b32 v215, v193, v215, s29
	v_bfi_b32 v32, v188, v222, s29
	v_bfi_b32 v34, v189, v223, s29
	v_bfi_b32 v216, v194, v216, s29
	v_bfi_b32 v35, v190, v224, s29
	v_bfi_b32 v213, v191, v225, s29
	v_bfi_b32 v217, v195, v217, s29
	v_max3_f32 v218, v214, v215, v32
	v_max3_f32 v220, v34, v216, v35
	v_max3_f32 v218, v218, v213, v217
	v_max_f32_e32 v218, v218, v220
	v_add_f32_e32 v219, 0x41000000, v172
	v_cmp_gt_f32_e32 vcc, v218, v219
	s_cbranch_vccz .LBB0_357
	v_mov_b32_e32 v219, v218
	s_nop 1
	v_permlane16_swap_b32 v218, v219
	s_nop 0
	v_max_f32_e32 v219, v219, v219
	v_max_f32_e32 v218, v218, v218
	v_max_f32_e32 v218, v218, v219
	v_mov_b32_e32 v219, v218
	s_nop 1
	v_permlane32_swap_b32 v219, v218
	s_nop 0
	v_max3_f32 v218, v172, v219, v218
	v_sub_f32_e32 v172, v172, v218
	v_exp_f32_e32 v172, v172
	s_nop 0
	v_pk_mul_f32 v[114:115], v[114:115], v[172:173] op_sel_hi:[1,0]
	v_pk_mul_f32 v[112:113], v[112:113], v[172:173] op_sel_hi:[1,0]
	v_pk_mul_f32 v[110:111], v[110:111], v[172:173] op_sel_hi:[1,0]
	v_pk_mul_f32 v[108:109], v[108:109], v[172:173] op_sel_hi:[1,0]
	v_pk_mul_f32 v[106:107], v[106:107], v[172:173] op_sel_hi:[1,0]
	v_pk_mul_f32 v[104:105], v[104:105], v[172:173] op_sel_hi:[1,0]
	v_pk_mul_f32 v[102:103], v[102:103], v[172:173] op_sel_hi:[1,0]
	v_pk_mul_f32 v[100:101], v[100:101], v[172:173] op_sel_hi:[1,0]
	v_pk_mul_f32 v[118:119], v[118:119], v[172:173] op_sel_hi:[1,0]
	v_pk_mul_f32 v[116:117], v[116:117], v[172:173] op_sel_hi:[1,0]
	v_mov_b32_e32 v172, v218
.LBB0_357:
	v_sub_f32_e32 v214, v214, v172
	v_exp_f32_e32 v218, v214
	v_sub_f32_e32 v214, v215, v172
	v_exp_f32_e32 v219, v214
	v_sub_f32_e32 v214, v216, v172
	v_sub_f32_e32 v32, v32, v172
	v_sub_f32_e32 v34, v34, v172
	v_sub_f32_e32 v35, v35, v172
	v_sub_f32_e32 v213, v213, v172
	v_exp_f32_e32 v220, v214
	v_sub_f32_e32 v214, v217, v172
	v_exp_f32_e32 v32, v32
	v_exp_f32_e32 v34, v34
	v_exp_f32_e32 v35, v35
	v_exp_f32_e32 v213, v213
	v_exp_f32_e32 v217, v214
	v_cvt_pk_bf16_f32 v214, v32, v34
	v_cvt_pk_bf16_f32 v216, v218, v219
	v_cvt_pk_bf16_f32 v215, v35, v213
	v_cvt_pk_bf16_f32 v217, v220, v217
	s_waitcnt vmcnt(11)
	s_nop 0
	v_mfma_f32_16x16x32_bf16 v[112:115], v[120:123], v[214:217], v[112:115]
	s_waitcnt vmcnt(10)
	v_mfma_f32_16x16x32_bf16 v[108:111], v[124:127], v[214:217], v[108:111]
	s_waitcnt vmcnt(9)
	v_mfma_f32_16x16x32_bf16 v[104:107], v[128:131], v[214:217], v[104:107]
	s_waitcnt vmcnt(8)
	v_mfma_f32_16x16x32_bf16 v[100:103], v[132:135], v[214:217], v[100:103]
	v_mfma_f32_16x16x32_bf16 v[116:119], v[36:39], v[214:217], v[116:119]
	ds_read_b128 v[214:217], v168 offset:24576
	ds_read_b128 v[218:221], v168 offset:25600
	ds_read_b32 v222, v212 offset:128
	ds_read_b32 v246, v212 offset:192
	ds_read_b32 v223, v212 offset:132
	ds_read_b32 v247, v212 offset:196
	ds_read_b32 v224, v212 offset:136
	ds_read_b32 v248, v212 offset:200
	ds_read_b32 v225, v212 offset:140
	ds_read_b32 v249, v212 offset:204
	s_waitcnt lgkmcnt(1)
	v_mfma_f32_16x16x32_bf16 v[222:225], v[136:139], v[214:217], v[222:225]
	s_waitcnt lgkmcnt(0)
	v_mfma_f32_16x16x32_bf16 v[214:217], v[148:151], v[214:217], v[246:249]
	v_readlane_b32 s60, v252, 47
	v_mfma_f32_16x16x32_bf16 v[222:225], v[140:143], v[218:221], v[222:225]
	v_mfma_f32_16x16x32_bf16 v[214:217], v[144:147], v[218:221], v[214:217]
	s_nop 6
	v_bfi_b32 v32, v196, v222, s29
	v_bfi_b32 v34, v197, v223, s29
	v_bfi_b32 v35, v198, v224, s29
	v_bfi_b32 v37, v199, v225, s29
	v_bfi_b32 v38, v200, v214, s29
	v_bfi_b32 v39, v201, v215, s29
	v_bfi_b32 v213, v202, v216, s29
	v_bfi_b32 v214, v203, v217, s29
	v_max3_f32 v215, v32, v34, v35
	v_max3_f32 v217, v37, v38, v39
	v_max3_f32 v215, v215, v213, v214
	v_max_f32_e32 v215, v215, v217
	v_add_f32_e32 v216, 0x41000000, v171
	v_cmp_gt_f32_e32 vcc, v215, v216
	s_cbranch_vccz .LBB0_359
	v_mov_b32_e32 v216, v215
	s_nop 1
	v_permlane16_swap_b32 v215, v216
	s_nop 0
	v_max_f32_e32 v216, v216, v216
	v_max_f32_e32 v215, v215, v215
	v_max_f32_e32 v215, v215, v216
	v_mov_b32_e32 v216, v215
	s_nop 1
	v_permlane32_swap_b32 v215, v216
	s_nop 0
	v_max3_f32 v215, v171, v215, v216
	v_sub_f32_e32 v171, v171, v215
	v_exp_f32_e32 v216, v171
	v_mov_b32_e32 v171, v215
	v_pk_mul_f32 v[94:95], v[94:95], v[216:217] op_sel_hi:[1,0]
	v_pk_mul_f32 v[92:93], v[92:93], v[216:217] op_sel_hi:[1,0]
	v_pk_mul_f32 v[90:91], v[90:91], v[216:217] op_sel_hi:[1,0]
	v_pk_mul_f32 v[88:89], v[88:89], v[216:217] op_sel_hi:[1,0]
	v_pk_mul_f32 v[86:87], v[86:87], v[216:217] op_sel_hi:[1,0]
	v_pk_mul_f32 v[84:85], v[84:85], v[216:217] op_sel_hi:[1,0]
	v_pk_mul_f32 v[82:83], v[82:83], v[216:217] op_sel_hi:[1,0]
	v_pk_mul_f32 v[80:81], v[80:81], v[216:217] op_sel_hi:[1,0]
	v_pk_mul_f32 v[98:99], v[98:99], v[216:217] op_sel_hi:[1,0]
	v_pk_mul_f32 v[96:97], v[96:97], v[216:217] op_sel_hi:[1,0]
.LBB0_359:
	v_sub_f32_e32 v35, v35, v171
	v_sub_f32_e32 v37, v37, v171
	v_sub_f32_e32 v38, v38, v171
	v_sub_f32_e32 v39, v39, v171
	v_exp_f32_e32 v35, v35
	v_exp_f32_e32 v37, v37
	v_exp_f32_e32 v38, v38
	v_exp_f32_e32 v39, v39
	v_sub_f32_e32 v32, v32, v171
	v_sub_f32_e32 v34, v34, v171
	v_sub_f32_e32 v213, v213, v171
	v_sub_f32_e32 v214, v214, v171
	v_exp_f32_e32 v32, v32
	v_exp_f32_e32 v34, v34
	v_exp_f32_e32 v213, v213
	v_exp_f32_e32 v217, v214
	v_cvt_pk_bf16_f32 v215, v35, v37
	v_cvt_pk_bf16_f32 v216, v38, v39
	v_mov_b32_e32 v37, v36
	v_mov_b32_e32 v38, v36
	v_mov_b32_e32 v39, v36
	v_cvt_pk_bf16_f32 v214, v32, v34
	v_cvt_pk_bf16_f32 v217, v213, v217
	s_nop 1
	v_mfma_f32_16x16x32_bf16 v[92:95], v[120:123], v[214:217], v[92:95]
	v_mfma_f32_16x16x32_bf16 v[88:91], v[124:127], v[214:217], v[88:91]
	v_mfma_f32_16x16x32_bf16 v[84:87], v[128:131], v[214:217], v[84:87]
	v_mfma_f32_16x16x32_bf16 v[80:83], v[132:135], v[214:217], v[80:83]
	v_mfma_f32_16x16x32_bf16 v[96:99], v[36:39], v[214:217], v[96:99]
	ds_read_b128 v[214:217], v168 offset:26624
	ds_read_b128 v[218:221], v168 offset:27648
	ds_read_b32 v222, v212 offset:64
	ds_read_b32 v246, v212 offset:128
	ds_read_b32 v223, v212 offset:68
	ds_read_b32 v247, v212 offset:132
	ds_read_b32 v224, v212 offset:72
	ds_read_b32 v248, v212 offset:136
	ds_read_b32 v225, v212 offset:76
	ds_read_b32 v249, v212 offset:140
	s_waitcnt lgkmcnt(1)
	v_mfma_f32_16x16x32_bf16 v[136:139], v[136:139], v[214:217], v[222:225]
	v_mfma_f32_16x16x32_bf16 v[136:139], v[140:143], v[218:221], v[136:139]
	s_waitcnt lgkmcnt(0)
	v_mfma_f32_16x16x32_bf16 v[140:143], v[148:151], v[214:217], v[246:249]
	v_mfma_f32_16x16x32_bf16 v[140:143], v[144:147], v[218:221], v[140:143]
	s_nop 4
	v_bfi_b32 v32, v204, v136, s29
	v_bfi_b32 v34, v205, v137, s29
	v_bfi_b32 v35, v206, v138, s29
	v_bfi_b32 v136, v207, v139, s29
	v_bfi_b32 v137, v208, v140, s29
	v_bfi_b32 v138, v209, v141, s29
	v_bfi_b32 v139, v210, v142, s29
	v_bfi_b32 v140, v211, v143, s29
	v_max3_f32 v141, v32, v34, v35
	v_max3_f32 v143, v136, v137, v138
	v_max3_f32 v141, v141, v139, v140
	v_max_f32_e32 v141, v141, v143
	v_add_f32_e32 v142, 0x41000000, v169
	v_cmp_gt_f32_e32 vcc, v141, v142
	s_cbranch_vccz .LBB0_348
	v_mov_b32_e32 v142, v141
	s_nop 1
	v_permlane16_swap_b32 v141, v142
	s_nop 0
	v_max_f32_e32 v142, v142, v142
	v_max_f32_e32 v141, v141, v141
	v_max_f32_e32 v141, v141, v142
	v_mov_b32_e32 v142, v141
	s_nop 1
	v_permlane32_swap_b32 v141, v142
	s_nop 0
	v_max3_f32 v141, v169, v141, v142
	v_sub_f32_e32 v142, v169, v141
	v_exp_f32_e32 v142, v142
	v_mov_b32_e32 v169, v141
	v_pk_mul_f32 v[54:55], v[54:55], v[142:143] op_sel_hi:[1,0]
	v_pk_mul_f32 v[52:53], v[52:53], v[142:143] op_sel_hi:[1,0]
	v_pk_mul_f32 v[50:51], v[50:51], v[142:143] op_sel_hi:[1,0]
	v_pk_mul_f32 v[48:49], v[48:49], v[142:143] op_sel_hi:[1,0]
	v_pk_mul_f32 v[46:47], v[46:47], v[142:143] op_sel_hi:[1,0]
	v_pk_mul_f32 v[44:45], v[44:45], v[142:143] op_sel_hi:[1,0]
	v_pk_mul_f32 v[42:43], v[42:43], v[142:143] op_sel_hi:[1,0]
	v_pk_mul_f32 v[40:41], v[40:41], v[142:143] op_sel_hi:[1,0]
	v_pk_mul_f32 v[58:59], v[58:59], v[142:143] op_sel_hi:[1,0]
	v_pk_mul_f32 v[56:57], v[56:57], v[142:143] op_sel_hi:[1,0]
	s_branch .LBB0_348
